# P0 weight-prep: nt loads, sc1 write-through stores, fewer transpose items for the 64 ssm_gen workgroups (13 vs 22 per wave); plus global_* ops and deferred SSQ atomics
# baseline (speedup 1.0000x reference)
; #define p_cvec INP(1)
; #define p_w_ada INP(3)
; __global__ void __launch_bounds__(NTHR, 2) mk_fwd(Args args) {
;     ...
;             for (int r = g0; r < I_MOD; r += gn) { const int sl = r / 72, cb = r % 72, col = cb * 256 + lane * 4; f32x4 acc = {0.f, 0.f, 0.f, 0.f};
;                 const float* wp = p_w_ada + (size_t)(sl * 64) * NMOD + col; const float* cp = p_cvec + sl * 64;
; #pragma unroll 16
;                 for (int kk = 0; kk < 64; ++kk) { const float cv = cp[kk]; const float sv = cv / (1.0f + expf(-cv)); acc += *(const f32x4*)(wp + (size_t)kk * NMOD) * sv; }
;                 *(f32x4*)(p_modp + (size_t)sl * NMOD + col) = acc; } }
.LBB0_110:
	v_mov_b64_e32 v[4:5], s[36:37]
	global_load_dwordx4 v[28:31], v[4:5], off nt
	global_load_dwordx4 v[12:15], v[4:5], off offset:16 nt
	global_load_dwordx4 v[8:11], v[4:5], off offset:32 nt
	v_lshl_add_u64 v[36:37], v[86:87], 0, s[38:39]
	v_add_co_u32_e32 v38, vcc, s41, v36
	global_load_dwordx4 v[4:7], v[4:5], off offset:48 nt
	s_nop 0
	v_addc_co_u32_e32 v39, vcc, 0, v37, vcc
	v_add_co_u32_e32 v94, vcc, s45, v36
	s_add_u32 s38, s38, 0x120000
	s_nop 0
	v_addc_co_u32_e32 v95, vcc, 0, v37, vcc
	v_add_co_u32_e32 v96, vcc, s46, v36
	s_addc_u32 s39, s39, 0
	s_nop 0
	v_addc_co_u32_e32 v97, vcc, 0, v37, vcc
	v_add_co_u32_e32 v98, vcc, s47, v36
	s_add_u32 s36, s36, 64
	s_nop 0
	v_addc_co_u32_e32 v99, vcc, 0, v37, vcc
	v_add_co_u32_e32 v100, vcc, s48, v36
	s_addc_u32 s37, s37, 0
	s_nop 0
	v_addc_co_u32_e32 v101, vcc, 0, v37, vcc
	v_add_co_u32_e32 v102, vcc, s49, v36
	s_cmp_eq_u32 s38, 0x480000
	s_nop 0
	v_addc_co_u32_e32 v103, vcc, 0, v37, vcc
	v_add_co_u32_e32 v104, vcc, s50, v36
	s_waitcnt vmcnt(0) lgkmcnt(0)
	v_mul_f32_e32 v93, 0xbfb8aa3b, v28
	v_addc_co_u32_e32 v105, vcc, 0, v37, vcc
	v_add_co_u32_e32 v106, vcc, s51, v36
	v_cmp_nlt_f32_e64 s[30:31], s43, v28
	s_nop 0
	v_addc_co_u32_e32 v107, vcc, 0, v37, vcc
	v_add_co_u32_e32 v108, vcc, s52, v36
	v_cmp_nlt_f32_e64 s[0:1], s43, v30
	s_nop 0
	v_addc_co_u32_e32 v109, vcc, 0, v37, vcc
	v_add_co_u32_e32 v110, vcc, s53, v36
	v_cmp_nlt_f32_e64 s[4:5], s43, v31
	s_nop 0
	v_addc_co_u32_e32 v111, vcc, 0, v37, vcc
	v_add_co_u32_e32 v112, vcc, s54, v36
	v_cmp_nlt_f32_e64 s[6:7], s43, v12
	s_nop 0
	v_addc_co_u32_e32 v113, vcc, 0, v37, vcc
	v_add_co_u32_e32 v114, vcc, s55, v36
	v_cmp_nlt_f32_e64 s[8:9], s43, v13
	s_nop 0
	v_addc_co_u32_e32 v115, vcc, 0, v37, vcc
	v_add_co_u32_e32 v116, vcc, s56, v36
	v_cmp_nlt_f32_e64 s[10:11], s43, v14
	s_nop 0
	v_addc_co_u32_e32 v117, vcc, 0, v37, vcc
	v_add_co_u32_e32 v118, vcc, s57, v36
	v_cmp_nlt_f32_e64 s[28:29], s43, v15
	s_nop 0
	v_addc_co_u32_e32 v119, vcc, 0, v37, vcc
	v_add_co_u32_e32 v120, vcc, s58, v36
	v_cmp_nlt_f32_e64 s[12:13], s43, v8
	s_nop 0
	v_addc_co_u32_e32 v121, vcc, 0, v37, vcc
	global_load_dwordx4 v[80:83], v[36:37], off nt
	global_load_dwordx4 v[76:79], v[38:39], off nt
	global_load_dwordx4 v[72:75], v[94:95], off nt
	global_load_dwordx4 v[68:71], v[96:97], off nt
	global_load_dwordx4 v[64:67], v[98:99], off nt
	global_load_dwordx4 v[60:63], v[100:101], off nt
	global_load_dwordx4 v[56:59], v[102:103], off nt
	global_load_dwordx4 v[52:55], v[104:105], off nt
	global_load_dwordx4 v[48:51], v[106:107], off nt
	global_load_dwordx4 v[44:47], v[108:109], off nt
	global_load_dwordx4 v[40:43], v[110:111], off nt
	global_load_dwordx4 v[32:35], v[112:113], off nt
	global_load_dwordx4 v[24:27], v[114:115], off nt
	global_load_dwordx4 v[20:23], v[116:117], off nt
	global_load_dwordx4 v[16:19], v[118:119], off nt
	global_load_dwordx4 v[36:39], v[120:121], off nt
	v_mul_f32_e32 v94, 0xbfb8aa3b, v29
	v_rndne_f32_e32 v109, v93
	v_fma_f32 v110, v28, s42, -v93
	v_mul_f32_e32 v95, 0xbfb8aa3b, v30
	v_rndne_f32_e32 v111, v94
	v_fma_f32 v112, v29, s42, -v94
	v_sub_f32_e32 v93, v93, v109
	v_fmac_f32_e32 v110, 0xb2a5705f, v28
	v_mul_f32_e32 v96, 0xbfb8aa3b, v31
	v_rndne_f32_e32 v113, v95
	v_fma_f32 v114, v30, s42, -v95
	v_sub_f32_e32 v94, v94, v111
	v_fmac_f32_e32 v112, 0xb2a5705f, v29
	v_add_f32_e32 v93, v93, v110
	v_mul_f32_e32 v97, 0xbfb8aa3b, v12
	v_rndne_f32_e32 v115, v96
	v_fma_f32 v116, v31, s42, -v96
	v_cvt_i32_f32_e32 v109, v109
	v_sub_f32_e32 v95, v95, v113
	v_fmac_f32_e32 v114, 0xb2a5705f, v30
	v_add_f32_e32 v94, v94, v112
	v_exp_f32_e32 v93, v93
	v_mul_f32_e32 v98, 0xbfb8aa3b, v13
	v_rndne_f32_e32 v117, v97
	v_fma_f32 v118, v12, s42, -v97
	v_cvt_i32_f32_e32 v111, v111
	v_sub_f32_e32 v96, v96, v115
	v_fmac_f32_e32 v116, 0xb2a5705f, v31
	v_add_f32_e32 v95, v95, v114
	v_exp_f32_e32 v94, v94
	v_mul_f32_e32 v99, 0xbfb8aa3b, v14
	v_rndne_f32_e32 v119, v98
	v_fma_f32 v120, v13, s42, -v98
	v_cvt_i32_f32_e32 v113, v113
	v_sub_f32_e32 v97, v97, v117
	v_fmac_f32_e32 v118, 0xb2a5705f, v12
	v_add_f32_e32 v96, v96, v116
	v_exp_f32_e32 v95, v95
	v_mul_f32_e32 v100, 0xbfb8aa3b, v15
	v_rndne_f32_e32 v121, v99
	v_fma_f32 v122, v14, s42, -v99
	v_cvt_i32_f32_e32 v115, v115
	v_sub_f32_e32 v98, v98, v119
	v_fmac_f32_e32 v120, 0xb2a5705f, v13
	v_add_f32_e32 v97, v97, v118
	v_exp_f32_e32 v96, v96
	v_mul_f32_e32 v101, 0xbfb8aa3b, v8
	v_rndne_f32_e32 v123, v100
	v_fma_f32 v124, v15, s42, -v100
	v_cvt_i32_f32_e32 v117, v117
	v_sub_f32_e32 v99, v99, v121
	v_fmac_f32_e32 v122, 0xb2a5705f, v14
	v_add_f32_e32 v98, v98, v120
	v_exp_f32_e32 v97, v97
	v_ldexp_f32 v93, v93, v109
	v_mul_f32_e32 v102, 0xbfb8aa3b, v9
	v_rndne_f32_e32 v125, v101
	v_fma_f32 v126, v8, s42, -v101
	v_cvt_i32_f32_e32 v119, v119
	v_sub_f32_e32 v100, v100, v123
	v_fmac_f32_e32 v124, 0xb2a5705f, v15
	v_add_f32_e32 v99, v99, v122
	v_exp_f32_e32 v98, v98
	v_ldexp_f32 v94, v94, v111
	v_cmp_nlt_f32_e32 vcc, s43, v29
	v_cndmask_b32_e64 v93, 0, v93, s[30:31]
	v_cmp_ngt_f32_e64 s[30:31], s44, v28
	v_mul_f32_e32 v103, 0xbfb8aa3b, v10
	v_rndne_f32_e32 v127, v102
	v_fma_f32 v128, v9, s42, -v102
	v_sub_f32_e32 v101, v101, v125
	v_fmac_f32_e32 v126, 0xb2a5705f, v8
	v_cvt_i32_f32_e32 v121, v121
	v_add_f32_e32 v100, v100, v124
	v_exp_f32_e32 v99, v99
	v_ldexp_f32 v95, v95, v113
	v_cndmask_b32_e32 v94, 0, v94, vcc
	v_cmp_ngt_f32_e32 vcc, s44, v29
	v_cndmask_b32_e64 v93, v92, v93, s[30:31]
	v_mul_f32_e32 v104, 0xbfb8aa3b, v11
	v_mul_f32_e32 v108, 0xbfb8aa3b, v7
	v_rndne_f32_e32 v129, v103
	v_fma_f32 v130, v10, s42, -v103
	v_sub_f32_e32 v102, v102, v127
	v_fmac_f32_e32 v128, 0xb2a5705f, v9
	v_cvt_i32_f32_e32 v123, v123
; __global__ void __launch_bounds__(NTHR, 2) mk_fwd(Args args) {
;     ...
;                 for (int kk = 0; kk < 64; ++kk) { const float cv = cp[kk]; const float sv = cv / (1.0f + expf(-cv)); acc += *(const f32x4*)(wp + (size_t)kk * NMOD) * sv; }
	v_add_f32_e32 v101, v101, v126
	v_exp_f32_e32 v100, v100
	v_ldexp_f32 v96, v96, v115
	v_cndmask_b32_e64 v95, 0, v95, s[0:1]
	v_cmp_ngt_f32_e64 s[0:1], s44, v30
	v_cndmask_b32_e32 v94, v92, v94, vcc
	v_add_f32_e32 v93, 1.0, v93
	v_mul_f32_e32 v105, 0xbfb8aa3b, v4
	v_mul_f32_e32 v107, 0xbfb8aa3b, v6
	v_rndne_f32_e32 v131, v104
	v_fma_f32 v132, v11, s42, -v104
	v_rndne_f32_e32 v139, v108
	v_fma_f32 v140, v7, s42, -v108
	v_sub_f32_e32 v103, v103, v129
	v_fmac_f32_e32 v130, 0xb2a5705f, v10
	v_cvt_i32_f32_e32 v125, v125
	v_add_f32_e32 v102, v102, v128
	v_exp_f32_e32 v101, v101
	v_ldexp_f32 v97, v97, v117
	v_cndmask_b32_e64 v96, 0, v96, s[4:5]
	v_cmp_ngt_f32_e64 s[4:5], s44, v31
	v_cndmask_b32_e64 v95, v92, v95, s[0:1]
	v_add_f32_e32 v94, 1.0, v94
	v_div_scale_f32 v109, s[0:1], v93, v93, v28
	v_mul_f32_e32 v106, 0xbfb8aa3b, v5
	v_rndne_f32_e32 v133, v105
	v_fma_f32 v134, v4, s42, -v105
	v_rndne_f32_e32 v137, v107
	v_fma_f32 v138, v6, s42, -v107
	v_sub_f32_e32 v104, v104, v131
	v_fmac_f32_e32 v132, 0xb2a5705f, v11
	v_sub_f32_e32 v108, v108, v139
	v_fmac_f32_e32 v140, 0xb2a5705f, v7
	v_cvt_i32_f32_e32 v127, v127
	v_add_f32_e32 v103, v103, v130
	v_exp_f32_e32 v102, v102
	v_ldexp_f32 v98, v98, v119
	v_cndmask_b32_e64 v97, 0, v97, s[6:7]
	v_cmp_ngt_f32_e64 s[6:7], s44, v12
	v_cndmask_b32_e64 v96, v92, v96, s[4:5]
	v_add_f32_e32 v95, 1.0, v95
	v_div_scale_f32 v111, s[0:1], v94, v94, v29
	v_rcp_f32_e32 v141, v109
	v_rndne_f32_e32 v135, v106
	v_fma_f32 v136, v5, s42, -v106
	v_sub_f32_e32 v105, v105, v133
	v_fmac_f32_e32 v134, 0xb2a5705f, v4
	v_sub_f32_e32 v107, v107, v137
	v_fmac_f32_e32 v138, 0xb2a5705f, v6
	v_cvt_i32_f32_e32 v129, v129
	v_add_f32_e32 v104, v104, v132
	v_add_f32_e32 v108, v108, v140
	v_exp_f32_e32 v103, v103
	v_ldexp_f32 v99, v99, v121
	v_cndmask_b32_e64 v98, 0, v98, s[8:9]
	v_cmp_ngt_f32_e64 s[8:9], s44, v13
	v_cndmask_b32_e64 v97, v92, v97, s[6:7]
	v_add_f32_e32 v96, 1.0, v96
	v_div_scale_f32 v113, s[0:1], v95, v95, v30
	v_rcp_f32_e32 v142, v111
	v_sub_f32_e32 v106, v106, v135
	v_fmac_f32_e32 v136, 0xb2a5705f, v5
	v_cvt_i32_f32_e32 v131, v131
	v_cvt_i32_f32_e32 v139, v139
	v_add_f32_e32 v105, v105, v134
	v_add_f32_e32 v107, v107, v138
	v_exp_f32_e32 v104, v104
	v_exp_f32_e32 v108, v108
	v_ldexp_f32 v100, v100, v123
	v_cndmask_b32_e64 v99, 0, v99, s[10:11]
	v_cmp_ngt_f32_e64 s[10:11], s44, v14
	v_cndmask_b32_e64 v98, v92, v98, s[8:9]
	v_add_f32_e32 v97, 1.0, v97
	v_div_scale_f32 v115, s[0:1], v96, v96, v31
	v_rcp_f32_e32 v143, v113
	v_cvt_i32_f32_e32 v133, v133
	v_cvt_i32_f32_e32 v137, v137
	v_add_f32_e32 v106, v106, v136
	v_exp_f32_e32 v105, v105
	v_exp_f32_e32 v107, v107
	v_ldexp_f32 v101, v101, v125
	v_cndmask_b32_e64 v100, 0, v100, s[28:29]
	v_cmp_ngt_f32_e64 s[28:29], s44, v15
	v_cndmask_b32_e64 v99, v92, v99, s[10:11]
	v_add_f32_e32 v98, 1.0, v98
	v_div_scale_f32 v117, s[0:1], v97, v97, v12
	v_rcp_f32_e32 v144, v115
	v_cvt_i32_f32_e32 v135, v135
	v_exp_f32_e32 v106, v106
	v_ldexp_f32 v102, v102, v127
	v_cmp_nlt_f32_e64 s[14:15], s43, v9
	v_cndmask_b32_e64 v101, 0, v101, s[12:13]
	v_cmp_ngt_f32_e64 s[12:13], s44, v8
	v_cndmask_b32_e64 v100, v92, v100, s[28:29]
	v_add_f32_e32 v99, 1.0, v99
	v_div_scale_f32 v119, s[0:1], v98, v98, v13
	v_rcp_f32_e32 v145, v117
	v_fma_f32 v157, -v109, v141, 1.0
	v_ldexp_f32 v103, v103, v129
	v_cmp_nlt_f32_e64 s[16:17], s43, v10
	v_cndmask_b32_e64 v102, 0, v102, s[14:15]
	v_cmp_ngt_f32_e64 s[14:15], s44, v9
	v_cndmask_b32_e64 v101, v92, v101, s[12:13]
	v_add_f32_e32 v100, 1.0, v100
	v_div_scale_f32 v110, vcc, v28, v93, v28
	v_div_scale_f32 v121, s[0:1], v99, v99, v14
	v_rcp_f32_e32 v146, v119
	v_fma_f32 v158, -v111, v142, 1.0
	v_fmac_f32_e32 v141, v157, v141
	v_ldexp_f32 v104, v104, v131
	v_ldexp_f32 v108, v108, v139
	v_cmp_nlt_f32_e64 s[18:19], s43, v11
	v_cmp_nlt_f32_e64 s[26:27], s43, v7
	v_cndmask_b32_e64 v103, 0, v103, s[16:17]
	v_cmp_ngt_f32_e64 s[16:17], s44, v10
	v_cndmask_b32_e64 v102, v92, v102, s[14:15]
	v_add_f32_e32 v101, 1.0, v101
	v_div_scale_f32 v112, s[30:31], v29, v94, v29
	v_div_scale_f32 v123, s[0:1], v100, v100, v15
	v_rcp_f32_e32 v147, v121
	v_fma_f32 v159, -v113, v143, 1.0
	v_fmac_f32_e32 v142, v158, v142
	v_mul_f32_e32 v157, v110, v141
	v_ldexp_f32 v105, v105, v133
	v_ldexp_f32 v107, v107, v137
	v_cmp_nlt_f32_e64 s[20:21], s43, v4
	v_cmp_nlt_f32_e64 s[24:25], s43, v6
	v_cndmask_b32_e64 v104, 0, v104, s[18:19]
	v_cmp_ngt_f32_e64 s[18:19], s44, v11
	v_cndmask_b32_e64 v108, 0, v108, s[26:27]
	v_cmp_ngt_f32_e64 s[26:27], s44, v7
	v_cndmask_b32_e64 v103, v92, v103, s[16:17]
	v_add_f32_e32 v102, 1.0, v102
	v_div_scale_f32 v114, s[28:29], v30, v95, v30
	v_div_scale_f32 v125, s[0:1], v101, v101, v8
	v_rcp_f32_e32 v148, v123
	v_fma_f32 v160, -v115, v144, 1.0
	v_fmac_f32_e32 v143, v159, v143
	v_mul_f32_e32 v158, v112, v142
	v_fma_f32 v173, -v109, v157, v110
	v_ldexp_f32 v106, v106, v135
	v_cmp_nlt_f32_e64 s[22:23], s43, v5
	v_cndmask_b32_e64 v105, 0, v105, s[20:21]
	v_cmp_ngt_f32_e64 s[20:21], s44, v4
	v_cndmask_b32_e64 v107, 0, v107, s[24:25]
	v_cmp_ngt_f32_e64 s[24:25], s44, v6
	v_cndmask_b32_e64 v104, v92, v104, s[18:19]
	v_cndmask_b32_e64 v108, v92, v108, s[26:27]
	v_add_f32_e32 v103, 1.0, v103
	v_div_scale_f32 v116, s[26:27], v31, v96, v31
	v_div_scale_f32 v127, s[0:1], v102, v102, v9
	v_rcp_f32_e32 v149, v125
	v_fma_f32 v161, -v117, v145, 1.0
	v_fmac_f32_e32 v144, v160, v144
	v_mul_f32_e32 v159, v114, v143
	v_fma_f32 v174, -v111, v158, v112
	v_fmac_f32_e32 v157, v173, v141
	v_cndmask_b32_e64 v106, 0, v106, s[22:23]
	v_cmp_ngt_f32_e64 s[22:23], s44, v5
	v_cndmask_b32_e64 v105, v92, v105, s[20:21]
	v_cndmask_b32_e64 v107, v92, v107, s[24:25]
	v_add_f32_e32 v104, 1.0, v104
; #define p_cvec INP(1)
; #define p_w_ada INP(3)
; __global__ void __launch_bounds__(NTHR, 2) mk_fwd(Args args) {
;     ...
;             for (int r = g0; r < I_MOD; r += gn) { const int sl = r / 72, cb = r % 72, col = cb * 256 + lane * 4; f32x4 acc = {0.f, 0.f, 0.f, 0.f};
;                 const float* wp = p_w_ada + (size_t)(sl * 64) * NMOD + col; const float* cp = p_cvec + sl * 64;
; #pragma unroll 16
;                 for (int kk = 0; kk < 64; ++kk) { const float cv = cp[kk]; const float sv = cv / (1.0f + expf(-cv)); acc += *(const f32x4*)(wp + (size_t)kk * NMOD) * sv; }
;                 *(f32x4*)(p_modp + (size_t)sl * NMOD + col) = acc; } }
	v_div_scale_f32 v118, s[24:25], v12, v97, v12
	v_div_scale_f32 v129, s[0:1], v103, v103, v10
	v_rcp_f32_e32 v150, v127
	v_fma_f32 v162, -v119, v146, 1.0
	v_fmac_f32_e32 v145, v161, v145
	v_mul_f32_e32 v160, v116, v144
	v_fma_f32 v175, -v113, v159, v114
	v_fmac_f32_e32 v158, v174, v142
	v_fma_f32 v109, -v109, v157, v110
	v_cndmask_b32_e64 v106, v92, v106, s[22:23]
	v_add_f32_e32 v105, 1.0, v105
	v_div_scale_f32 v120, s[22:23], v13, v98, v13
	v_div_scale_f32 v131, s[0:1], v104, v104, v11
	v_rcp_f32_e32 v151, v129
	v_fma_f32 v163, -v121, v147, 1.0
	v_fmac_f32_e32 v146, v162, v146
	v_mul_f32_e32 v161, v118, v145
	v_fma_f32 v176, -v115, v160, v116
	v_fmac_f32_e32 v159, v175, v143
	v_fma_f32 v110, -v111, v158, v112
	v_div_fmas_f32 v109, v109, v141, v157
	s_mov_b64 vcc, s[30:31]
	v_add_f32_e32 v106, 1.0, v106
	v_div_scale_f32 v122, s[20:21], v14, v99, v14
	v_div_scale_f32 v133, s[0:1], v105, v105, v4
	v_rcp_f32_e32 v152, v131
	v_fma_f32 v164, -v123, v148, 1.0
	v_fmac_f32_e32 v147, v163, v147
	v_mul_f32_e32 v162, v120, v146
	v_fma_f32 v177, -v117, v161, v118
	v_fmac_f32_e32 v160, v176, v144
	v_fma_f32 v111, -v113, v159, v114
	v_div_fixup_f32 v28, v109, v93, v28
	v_div_fmas_f32 v93, v110, v142, v158
	s_mov_b64 vcc, s[28:29]
	v_add_f32_e32 v107, 1.0, v107
	v_div_scale_f32 v124, s[18:19], v15, v100, v15
	v_div_scale_f32 v135, s[0:1], v106, v106, v5
	v_rcp_f32_e32 v153, v133
	v_fma_f32 v165, -v125, v149, 1.0
	v_fmac_f32_e32 v148, v164, v148
	v_mul_f32_e32 v163, v122, v147
	v_fma_f32 v178, -v119, v162, v120
	v_fmac_f32_e32 v161, v177, v145
	v_fma_f32 v112, -v115, v160, v116
	s_waitcnt vmcnt(0) lgkmcnt(0)
	v_pk_fma_f32 v[0:1], v[80:81], v[28:29], v[0:1] op_sel_hi:[1,0,1]
	v_pk_fma_f32 v[2:3], v[82:83], v[28:29], v[2:3] op_sel_hi:[1,0,1]
	v_div_fixup_f32 v28, v93, v94, v29
	v_div_fmas_f32 v29, v111, v143, v159
	s_mov_b64 vcc, s[26:27]
	v_add_f32_e32 v108, 1.0, v108
	v_div_scale_f32 v126, s[16:17], v8, v101, v8
	v_div_scale_f32 v137, s[0:1], v107, v107, v6
	v_rcp_f32_e32 v154, v135
	v_fma_f32 v166, -v127, v150, 1.0
	v_fmac_f32_e32 v149, v165, v149
	v_mul_f32_e32 v164, v124, v148
	v_fma_f32 v179, -v121, v163, v122
	v_fmac_f32_e32 v162, v178, v146
	v_fma_f32 v113, -v117, v161, v118
	v_pk_fma_f32 v[2:3], v[78:79], v[28:29], v[2:3] op_sel_hi:[1,0,1]
	v_pk_fma_f32 v[0:1], v[76:77], v[28:29], v[0:1] op_sel_hi:[1,0,1]
	v_div_fixup_f32 v28, v29, v95, v30
	v_div_fmas_f32 v29, v112, v144, v160
	s_mov_b64 vcc, s[24:25]
	v_div_scale_f32 v128, s[14:15], v9, v102, v9
	v_div_scale_f32 v139, s[0:1], v108, v108, v7
	v_rcp_f32_e32 v155, v137
	v_fma_f32 v167, -v129, v151, 1.0
	v_fmac_f32_e32 v150, v166, v150
	v_mul_f32_e32 v165, v126, v149
	v_fma_f32 v180, -v123, v164, v124
	v_fmac_f32_e32 v163, v179, v147
	v_fma_f32 v114, -v119, v162, v120
	v_pk_fma_f32 v[0:1], v[72:73], v[28:29], v[0:1] op_sel_hi:[1,0,1]
	v_pk_fma_f32 v[2:3], v[74:75], v[28:29], v[2:3] op_sel_hi:[1,0,1]
	v_div_fixup_f32 v28, v29, v96, v31
	v_div_fmas_f32 v29, v113, v145, v161
	s_mov_b64 vcc, s[22:23]
	v_div_scale_f32 v130, s[12:13], v10, v103, v10
	v_rcp_f32_e32 v156, v139
	v_fma_f32 v168, -v131, v152, 1.0
	v_fmac_f32_e32 v151, v167, v151
	v_mul_f32_e32 v166, v128, v150
	v_fma_f32 v181, -v125, v165, v126
	v_fmac_f32_e32 v164, v180, v148
	v_fma_f32 v115, -v121, v163, v122
	v_pk_fma_f32 v[2:3], v[70:71], v[28:29], v[2:3] op_sel_hi:[1,0,1]
	v_pk_fma_f32 v[0:1], v[68:69], v[28:29], v[0:1] op_sel_hi:[1,0,1]
	v_div_fixup_f32 v12, v29, v97, v12
	v_div_fmas_f32 v28, v114, v146, v162
	s_mov_b64 vcc, s[20:21]
	v_div_scale_f32 v132, s[10:11], v11, v104, v11
	v_fma_f32 v169, -v133, v153, 1.0
	v_fmac_f32_e32 v152, v168, v152
	v_mul_f32_e32 v167, v130, v151
	v_fma_f32 v182, -v127, v166, v128
	v_fmac_f32_e32 v165, v181, v149
	v_fma_f32 v116, -v123, v164, v124
	v_pk_fma_f32 v[0:1], v[64:65], v[12:13], v[0:1] op_sel_hi:[1,0,1]
	v_pk_fma_f32 v[2:3], v[66:67], v[12:13], v[2:3] op_sel_hi:[1,0,1]
	v_div_fixup_f32 v12, v28, v98, v13
	v_div_fmas_f32 v13, v115, v147, v163
	s_mov_b64 vcc, s[18:19]
	v_div_scale_f32 v134, s[8:9], v4, v105, v4
	v_fma_f32 v170, -v135, v154, 1.0
	v_fmac_f32_e32 v153, v169, v153
	v_mul_f32_e32 v168, v132, v152
	v_fma_f32 v183, -v129, v167, v130
	v_fmac_f32_e32 v166, v182, v150
	v_fma_f32 v117, -v125, v165, v126
	v_pk_fma_f32 v[2:3], v[62:63], v[12:13], v[2:3] op_sel_hi:[1,0,1]
	v_pk_fma_f32 v[0:1], v[60:61], v[12:13], v[0:1] op_sel_hi:[1,0,1]
	v_div_fixup_f32 v12, v13, v99, v14
	v_div_fmas_f32 v13, v116, v148, v164
	s_mov_b64 vcc, s[16:17]
	v_div_scale_f32 v136, s[6:7], v5, v106, v5
	v_fma_f32 v171, -v137, v155, 1.0
	v_fmac_f32_e32 v154, v170, v154
	v_mul_f32_e32 v169, v134, v153
	v_fma_f32 v184, -v131, v168, v132
; #define p_cvec INP(1)
; #define p_w_ada INP(3)
; __global__ void __launch_bounds__(NTHR, 2) mk_fwd(Args args) {
;     ...
;         if (bx >= 64 || G <= 64) { const int g0 = (G > 64) ? gw - 64 * NWAVES : gw, gn = (G > 64) ? NGW - 64 * NWAVES : NGW;
;             for (int r = g0; r < I_MOD; r += gn) { const int sl = r / 72, cb = r % 72, col = cb * 256 + lane * 4; f32x4 acc = {0.f, 0.f, 0.f, 0.f};
;                 const float* wp = p_w_ada + (size_t)(sl * 64) * NMOD + col; const float* cp = p_cvec + sl * 64;
; #pragma unroll 16
;                 for (int kk = 0; kk < 64; ++kk) { const float cv = cp[kk]; const float sv = cv / (1.0f + expf(-cv)); acc += *(const f32x4*)(wp + (size_t)kk * NMOD) * sv; }
;                 *(f32x4*)(p_modp + (size_t)sl * NMOD + col) = acc; } }
;     ...
;         if (gw < NTR) { TrItem cur, nxt; f32x4 ra[8], rb[8]; int it = gw; P0_DECODE(it, cur); tr_load(cur, lane, ra);
	v_fmac_f32_e32 v167, v183, v151
	v_fma_f32 v118, -v127, v166, v128
	v_pk_fma_f32 v[0:1], v[56:57], v[12:13], v[0:1] op_sel_hi:[1,0,1]
	v_pk_fma_f32 v[2:3], v[58:59], v[12:13], v[2:3] op_sel_hi:[1,0,1]
	v_div_fixup_f32 v12, v13, v100, v15
	v_div_fmas_f32 v13, v117, v149, v165
	s_mov_b64 vcc, s[14:15]
	v_div_scale_f32 v138, s[4:5], v6, v107, v6
	v_fma_f32 v172, -v139, v156, 1.0
	v_fmac_f32_e32 v155, v171, v155
	v_mul_f32_e32 v170, v136, v154
	v_fma_f32 v185, -v133, v169, v134
	v_fmac_f32_e32 v168, v184, v152
	v_fma_f32 v119, -v129, v167, v130
	v_pk_fma_f32 v[2:3], v[54:55], v[12:13], v[2:3] op_sel_hi:[1,0,1]
	v_pk_fma_f32 v[0:1], v[52:53], v[12:13], v[0:1] op_sel_hi:[1,0,1]
	v_div_fixup_f32 v8, v13, v101, v8
	v_div_fmas_f32 v12, v118, v150, v166
	s_mov_b64 vcc, s[12:13]
	v_div_scale_f32 v140, s[0:1], v7, v108, v7
	v_fmac_f32_e32 v156, v172, v156
	v_mul_f32_e32 v171, v138, v155
	v_fma_f32 v186, -v135, v170, v136
	v_fmac_f32_e32 v169, v185, v153
	v_fma_f32 v120, -v131, v168, v132
	v_pk_fma_f32 v[0:1], v[48:49], v[8:9], v[0:1] op_sel_hi:[1,0,1]
	v_pk_fma_f32 v[2:3], v[50:51], v[8:9], v[2:3] op_sel_hi:[1,0,1]
	v_div_fixup_f32 v8, v12, v102, v9
	v_div_fmas_f32 v9, v119, v151, v167
	s_mov_b64 vcc, s[10:11]
	v_mul_f32_e32 v172, v140, v156
	v_fma_f32 v187, -v137, v171, v138
	v_fmac_f32_e32 v170, v186, v154
	v_fma_f32 v121, -v133, v169, v134
	v_pk_fma_f32 v[2:3], v[46:47], v[8:9], v[2:3] op_sel_hi:[1,0,1]
	v_pk_fma_f32 v[0:1], v[44:45], v[8:9], v[0:1] op_sel_hi:[1,0,1]
	v_div_fmas_f32 v12, v120, v152, v168
	v_div_fixup_f32 v8, v9, v103, v10
	s_mov_b64 vcc, s[8:9]
	v_fma_f32 v188, -v139, v172, v140
	v_fmac_f32_e32 v171, v187, v155
	v_fma_f32 v122, -v135, v170, v136
	v_pk_fma_f32 v[0:1], v[40:41], v[8:9], v[0:1] op_sel_hi:[1,0,1]
	v_pk_fma_f32 v[2:3], v[42:43], v[8:9], v[2:3] op_sel_hi:[1,0,1]
	v_div_fixup_f32 v8, v12, v104, v11
	v_div_fmas_f32 v9, v121, v153, v169
	s_mov_b64 vcc, s[6:7]
	v_fmac_f32_e32 v172, v188, v156
	v_fma_f32 v123, -v137, v171, v138
	v_pk_fma_f32 v[2:3], v[34:35], v[8:9], v[2:3] op_sel_hi:[1,0,1]
	v_pk_fma_f32 v[0:1], v[32:33], v[8:9], v[0:1] op_sel_hi:[1,0,1]
	v_div_fixup_f32 v4, v9, v105, v4
	v_div_fmas_f32 v8, v122, v154, v170
	s_mov_b64 vcc, s[4:5]
	v_fma_f32 v124, -v139, v172, v140
	v_pk_fma_f32 v[0:1], v[24:25], v[4:5], v[0:1] op_sel_hi:[1,0,1]
	v_pk_fma_f32 v[2:3], v[26:27], v[4:5], v[2:3] op_sel_hi:[1,0,1]
	v_div_fixup_f32 v4, v8, v106, v5
	v_div_fmas_f32 v5, v123, v155, v171
	s_mov_b64 vcc, s[0:1]
	v_pk_fma_f32 v[2:3], v[22:23], v[4:5], v[2:3] op_sel_hi:[1,0,1]
	v_pk_fma_f32 v[0:1], v[20:21], v[4:5], v[0:1] op_sel_hi:[1,0,1]
	v_div_fixup_f32 v4, v5, v107, v6
	v_div_fmas_f32 v5, v124, v156, v172
	v_pk_fma_f32 v[0:1], v[16:17], v[4:5], v[0:1] op_sel_hi:[1,0,1]
	v_pk_fma_f32 v[2:3], v[18:19], v[4:5], v[2:3] op_sel_hi:[1,0,1]
	v_div_fixup_f32 v4, v5, v108, v7
	v_pk_fma_f32 v[2:3], v[38:39], v[4:5], v[2:3] op_sel_hi:[1,0,1]
	v_pk_fma_f32 v[0:1], v[36:37], v[4:5], v[0:1] op_sel_hi:[1,0,1]
	s_cbranch_scc0 .LBB0_110
	v_mov_b32_e32 v4, s59
	ds_read_b64 v[4:5], v4
	s_mul_hi_i32 s1, s60, 0x12000
	s_mul_i32 s60, s60, 0x12000
	s_waitcnt lgkmcnt(0)
	v_readfirstlane_b32 s0, v4
	v_readfirstlane_b32 s4, v5
	s_add_u32 s0, s0, s60
	s_addc_u32 s1, s4, s1
	v_lshl_add_u64 v[4:5], v[84:85], 2, s[0:1]
	v_add_co_u32_e32 v4, vcc, 0x100000, v4
	s_add_i32 s3, s3, s40
	s_nop 0
	v_addc_co_u32_e32 v5, vcc, 0, v5, vcc
	s_cmpk_gt_i32 s3, 0x8ff
	global_store_dwordx4 v[4:5], v[0:3], off sc1
	s_cbranch_scc0 .LBB0_109
.LBB0_112:
	s_mov_b32 s81, s72
	s_mov_b32 s82, s80
	s_mov_b32 s83, 0x9e00
	s_cmpk_lg_i32 s70, 0x100
	s_cbranch_scc1 .Lp0_rb_done
	s_add_i32 s81, s72, 0xfffffe00
	s_movk_i32 s82, 0x600
	s_mov_b32 s83, 33792
	s_cmp_gt_i32 s2, 63
	s_cbranch_scc1 .Lp0_rb_done
	s_add_i32 s81, s72, 33792
	s_movk_i32 s82, 0x200
	s_mov_b32 s83, 0x9e00
.Lp0_rb_done:
	s_cmp_ge_i32 s81, s83
	s_cbranch_scc1 .LBB0_211
	s_cmpk_gt_i32 s81, 0x15ff
	s_cbranch_scc0 .LBB0_122
	s_cmpk_gt_u32 s81, 0x2bff
	s_cbranch_scc0 .LBB0_123
	s_cmpk_gt_u32 s81, 0x41ff
	s_cbranch_scc0 .LBB0_124
	s_cmpk_gt_u32 s81, 0x51ff
	s_cbranch_scc0 .LBB0_125
	s_cmpk_gt_u32 s81, 0x53ff
	s_cbranch_scc0 .LBB0_126
	s_cmpk_gt_u32 s81, 0x5bff
	s_cbranch_scc0 .LBB0_127
	s_cmpk_gt_u32 s81, 0x71ff
	s_cbranch_scc0 .LBB0_128
	s_add_i32 s0, 0, 0x20118
	v_mov_b32_e32 v0, s0
	ds_read_b64 v[0:1], v0
	s_cmpk_gt_u32 s81, 0x87ff
	s_mov_b32 s20, 0
	s_cbranch_scc0 .LBB0_129
	s_add_i32 s0, 0, 0x20108
	v_mov_b32_e32 v2, s0
	ds_read_b64 v[2:3], v2
	s_add_i32 s3, s81, 0xffff7800
	s_waitcnt lgkmcnt(0)
	v_readfirstlane_b32 s7, v0
	v_readfirstlane_b32 s10, v1
	s_mov_b64 s[4:5], 0
	v_readfirstlane_b32 s0, v2
	v_readfirstlane_b32 s1, v3
	s_branch .LBB0_130

.LBB0_130:
	s_andn2_b64 vcc, exec, s[4:5]
	s_cbranch_vccnz .LBB0_132
	s_add_i32 s0, 0, 0x20100
	v_mov_b32_e32 v2, s0
	ds_read_b64 v[2:3], v2
	s_add_i32 s3, s81, 0xffff8e00
	s_waitcnt lgkmcnt(0)
	v_readfirstlane_b32 s7, v0
	v_readfirstlane_b32 s10, v1
	s_mov_b64 s[4:5], 0x5200000
	v_readfirstlane_b32 s0, v2
	v_readfirstlane_b32 s1, v3
	s_movk_i32 s21, 0x800
	s_movk_i32 s6, 0x1600
	s_mov_b32 s20, 2
	s_branch .LBB0_133

.LBB0_134:
	s_andn2_b64 vcc, exec, s[8:9]
	s_cbranch_vccnz .LBB0_136
	s_add_i32 s0, 0, 0x200f8
	s_waitcnt lgkmcnt(0)
	v_mov_b32_e32 v0, s0
	s_add_i32 s0, 0, 0x20118
	v_mov_b32_e32 v2, s0
	ds_read_b64 v[0:1], v0
	ds_read_b64 v[2:3], v2
	s_add_i32 s3, s81, 0xffffa400
	s_mov_b64 s[4:5], 0x5200000
	s_movk_i32 s21, 0x800
	s_waitcnt lgkmcnt(0)
	v_readfirstlane_b32 s0, v0
	v_readfirstlane_b32 s1, v1
	v_readfirstlane_b32 s7, v2
	v_readfirstlane_b32 s10, v3
	s_movk_i32 s6, 0x1600
	s_mov_b32 s20, 1

.LBB0_137:
	s_andn2_b64 vcc, exec, s[8:9]
	s_cbranch_vccnz .LBB0_139
	s_add_i32 s0, 0, 0x200e8
	s_waitcnt lgkmcnt(0)
	v_mov_b32_e32 v0, s0
	s_add_i32 s0, 0, 0x20118
	v_mov_b32_e32 v2, s0
	ds_read_b64 v[0:1], v0
	ds_read_b64 v[2:3], v2
	s_add_i32 s3, s81, 0xffffac00
	s_mov_b32 s20, 0
	s_mov_b64 s[4:5], 0xa400000
	s_waitcnt lgkmcnt(0)
	v_readfirstlane_b32 s0, v0
	v_readfirstlane_b32 s1, v1
	v_readfirstlane_b32 s7, v2
	v_readfirstlane_b32 s10, v3
	s_movk_i32 s6, 0x800
	s_movk_i32 s21, 0x800

.LBB0_140:
	s_andn2_b64 vcc, exec, s[8:9]
	s_cbranch_vccnz .LBB0_142
	s_add_i32 s0, 0, 0x200d0
	s_waitcnt lgkmcnt(0)
	v_mov_b32_e32 v0, s0
	s_add_i32 s0, 0, 0x20118
	v_mov_b32_e32 v2, s0
	ds_read_b64 v[0:1], v0
	ds_read_b64 v[2:3], v2
	s_add_i32 s3, s81, 0xffffae00
	s_mov_b32 s20, 0
	s_mov_b64 s[4:5], 0xac00000
	s_waitcnt lgkmcnt(0)
	v_readfirstlane_b32 s0, v0
	v_readfirstlane_b32 s1, v1
	v_readfirstlane_b32 s7, v2
	v_readfirstlane_b32 s10, v3
	s_movk_i32 s6, 0x400
	s_movk_i32 s21, 0x400

.LBB0_143:
	s_andn2_b64 vcc, exec, s[8:9]
	s_cbranch_vccnz .LBB0_145
	s_add_i32 s0, 0, 0x20050
	s_waitcnt lgkmcnt(0)
	v_mov_b32_e32 v0, s0
	s_add_i32 s0, 0, 0x20118
	v_mov_b32_e32 v2, s0
	ds_read_b64 v[0:1], v0
	ds_read_b64 v[2:3], v2
	s_add_i32 s3, s81, 0xffffbe00
	s_mov_b64 s[4:5], 0x9400000
	s_movk_i32 s21, 0x800
	s_waitcnt lgkmcnt(0)
	v_readfirstlane_b32 s0, v0
	v_readfirstlane_b32 s1, v1
	v_readfirstlane_b32 s7, v2
	v_readfirstlane_b32 s10, v3
	s_movk_i32 s6, 0x1000
	s_mov_b32 s20, 3

.LBB0_146:
	s_andn2_b64 vcc, exec, s[8:9]
	s_cbranch_vccnz .LBB0_148
	s_add_i32 s0, 0, 0x20040
	s_waitcnt lgkmcnt(0)
	v_mov_b32_e32 v0, s0
	s_add_i32 s0, 0, 0x20118
	v_mov_b32_e32 v2, s0
	ds_read_b64 v[0:1], v0
	ds_read_b64 v[2:3], v2
	s_add_i32 s3, s81, 0xffffd400
	s_mov_b32 s20, 0
	s_mov_b64 s[4:5], 0x3c00000
	s_waitcnt lgkmcnt(0)
	v_readfirstlane_b32 s0, v0
	v_readfirstlane_b32 s1, v1
	v_readfirstlane_b32 s7, v2
	v_readfirstlane_b32 s10, v3
	s_movk_i32 s21, 0x1600
	s_movk_i32 s6, 0x800

.LBB0_149:
	s_add_i32 s0, 0, 0x20038
	s_waitcnt lgkmcnt(0)
	v_mov_b32_e32 v0, s0
	s_add_i32 s0, 0, 0x20118
	v_mov_b32_e32 v2, s0
	ds_read_b64 v[0:1], v0
	ds_read_b64 v[2:3], v2
	s_add_i32 s3, s81, 0xffffea00
	s_mov_b64 s[4:5], 0x1000000
	s_movk_i32 s21, 0x800
	s_waitcnt lgkmcnt(0)
	v_readfirstlane_b32 s0, v0
	v_readfirstlane_b32 s1, v1
	v_readfirstlane_b32 s7, v2
	v_readfirstlane_b32 s10, v3
	s_movk_i32 s6, 0x1600
	s_mov_b32 s20, 2

; __device__ __forceinline__ void tr_load(const TrItem& t, int lane, f32x4 (&r)[8]) {
;     const int nblk = t.N / 32, kb = t.item / nblk, nb = t.item % nblk;
;     const float* p = t.W + (size_t)(64 * kb + (lane >> 3)) * t.N + 32 * nb + (lane & 7) * 4;
; #pragma unroll
;     for (int i = 0; i < 8; ++i) r[i] = *(const f32x4*)(p + (size_t)(8 * i) * t.N);
; }
; __global__ void __launch_bounds__(NTHR, 2) mk_fwd(Args args) {
;     ...
;         if (gw < NTR) { TrItem cur, nxt; f32x4 ra[8], rb[8]; int it = gw; P0_DECODE(it, cur); tr_load(cur, lane, ra);
.LBB0_151:
	s_add_i32 s0, 0, 0x20030
	s_waitcnt lgkmcnt(0)
	v_mov_b32_e32 v0, s0
	s_add_i32 s0, 0, 0x20118
	v_mov_b32_e32 v2, s0
	ds_read_b64 v[0:1], v0
	ds_read_b64 v[2:3], v2
	s_movk_i32 s6, 0x1600
	s_movk_i32 s21, 0x800
	s_mov_b64 s[4:5], 0x1000000
	s_waitcnt lgkmcnt(0)
	v_readfirstlane_b32 s0, v0
	v_readfirstlane_b32 s1, v1
	v_readfirstlane_b32 s7, v2
	v_readfirstlane_b32 s10, v3
	s_mov_b32 s20, 1
	s_mov_b32 s3, s81
.LBB0_152:
	s_lshl_b32 s8, s93, 14
	s_add_i32 s11, s8, 0
	s_add_u32 s8, s7, s4
	s_addc_u32 s9, s10, s5
	s_lshr_b32 s4, s6, 5
	s_waitcnt lgkmcnt(0)
	v_cvt_f32_u32_e32 v0, s4
	s_sub_i32 s12, 0, s4
	s_abs_i32 s10, s3
	s_ashr_i32 s5, s3, 31
	v_rcp_iflag_f32_e32 v0, v0
	v_ashrrev_i32_e32 v76, 3, v88
	s_mov_b32 s7, 0
	v_mov_b32_e32 v65, 0
	v_mul_f32_e32 v0, 0x4f7ffffe, v0
	v_cvt_u32_f32_e32 v0, v0
	v_add_u32_e32 v77, 8, v76
	v_add_u32_e32 v78, 16, v76
	v_add_u32_e32 v79, 24, v76
	v_readfirstlane_b32 s13, v0
	s_mul_i32 s12, s12, s13
	s_mul_hi_u32 s12, s13, s12
	s_add_i32 s13, s13, s12
	s_mul_hi_u32 s12, s10, s13
	s_mul_i32 s13, s12, s4
	s_sub_i32 s10, s10, s13
	s_add_i32 s14, s12, 1
	s_sub_i32 s13, s10, s4
	s_cmp_ge_u32 s10, s4
	s_cselect_b32 s12, s14, s12
	s_cselect_b32 s10, s13, s10
	s_add_i32 s13, s12, 1
	s_cmp_ge_u32 s10, s4
	s_cselect_b32 s10, s13, s12
	s_xor_b32 s10, s10, s5
	s_sub_i32 s5, s10, s5
	s_mul_i32 s4, s5, s4
	v_lshl_add_u32 v0, s5, 6, v76
	s_sub_i32 s10, s3, s4
	v_ashrrev_i32_e32 v3, 31, v0
	v_mad_u64_u32 v[0:1], s[4:5], v0, s6, 0
	v_mov_b32_e32 v2, v1
	v_mad_u64_u32 v[2:3], s[4:5], v3, s6, v[2:3]
	v_mov_b32_e32 v1, v2
	v_lshl_add_u64 v[0:1], v[0:1], 2, s[0:1]
	s_lshl_b32 s0, s10, 5
	v_lshlrev_b32_e32 v2, 2, v88
	s_ashr_i32 s1, s0, 31
	v_and_b32_e32 v32, 28, v2
	v_lshl_add_u64 v[0:1], s[0:1], 2, v[0:1]
	v_lshlrev_b32_e32 v64, 2, v32
	v_lshl_add_u64 v[8:9], v[0:1], 0, v[64:65]
	s_lshl_b64 s[0:1], s[6:7], 5
	v_lshl_add_u64 v[10:11], v[8:9], 0, s[0:1]
	v_lshl_add_u64 v[16:17], v[10:11], 0, s[0:1]
	v_lshl_add_u64 v[18:19], v[16:17], 0, s[0:1]
	v_lshl_add_u64 v[24:25], v[18:19], 0, s[0:1]
	v_lshl_add_u64 v[26:27], v[24:25], 0, s[0:1]
	v_lshl_add_u64 v[34:35], v[26:27], 0, s[0:1]
	global_load_dwordx4 v[0:3], v[8:9], off nt
	global_load_dwordx4 v[4:7], v[10:11], off nt
	s_nop 0
	global_load_dwordx4 v[8:11], v[16:17], off nt
	global_load_dwordx4 v[12:15], v[18:19], off nt
	s_nop 0
	global_load_dwordx4 v[16:19], v[24:25], off nt
	global_load_dwordx4 v[20:23], v[26:27], off nt
	v_lshl_add_u64 v[36:37], v[34:35], 0, s[0:1]
	global_load_dwordx4 v[24:27], v[34:35], off nt
	global_load_dwordx4 v[28:31], v[36:37], off nt
	v_lshlrev_b32_e32 v34, 3, v88
	s_movk_i32 s0, 0x84
	v_and_b32_e32 v34, 56, v34
	v_add_u32_e32 v33, s11, v64
	v_mul_lo_u32 v35, v76, s0
	v_mul_u32_u24_e32 v36, 0x84, v34
	v_lshlrev_b32_e32 v37, 2, v76
	v_add3_u32 v80, s11, v36, v37
	v_and_b32_e32 v81, 31, v76
	v_and_b32_e32 v82, 31, v77
	v_and_b32_e32 v83, 31, v78
	v_and_b32_e32 v84, 31, v79
	s_add_i32 s22, 0, 0x20118
	s_add_i32 s23, 0, 0x20108
	s_add_i32 s24, 0, 0x20100
	s_add_i32 s25, 0, 0x200f8
	s_add_i32 s26, 0, 0x200e8
	s_add_i32 s27, 0, 0x200d0
	s_add_i32 s28, 0, 0x20050
	s_add_i32 s29, 0, 0x20040
	s_add_i32 s30, 0, 0x20038
	s_add_i32 s31, 0, 0x20030
	v_lshlrev_b32_e32 v66, 2, v32
	v_add_u32_e32 v85, v33, v35
	s_movk_i32 s36, 0xff00
	s_movk_i32 s37, 0x800
	s_movk_i32 s38, 0x7fff
	s_mov_b32 s39, 0xffff0000
	v_lshlrev_b32_e32 v64, 1, v34
	s_mov_b32 s40, s6
	s_mov_b32 s41, s81
	s_branch .LBB0_154

; __global__ void __launch_bounds__(NTHR, 2) mk_fwd(Args args) {
;     ...
;         if (gw < NTR) { TrItem cur, nxt; f32x4 ra[8], rb[8]; int it = gw; P0_DECODE(it, cur); tr_load(cur, lane, ra);
;             for (;;) { const int itn = it + NGW; const bool has = itn < NTR;
;                 if (has) { P0_DECODE(itn, nxt); tr_load(nxt, lane, rb); }
.LBB0_154:
	s_add_i32 s42, s41, s82
	s_cmp_lt_i32 s42, s83
	s_cselect_b64 s[12:13], -1, 0
	s_cmp_ge_i32 s42, s83
	s_cselect_b64 s[10:11], -1, 0
	s_and_b64 vcc, exec, s[10:11]
	s_cbranch_vccnz .LBB0_189
	s_cmpk_gt_i32 s42, 0x15ff
	s_mov_b64 s[14:15], -1
	s_cbranch_scc0 .LBB0_186
	s_cmpk_gt_u32 s42, 0x2bff
	s_cbranch_scc0 .LBB0_183
	s_cmpk_gt_u32 s42, 0x41ff
	s_cbranch_scc0 .LBB0_180
	s_cmpk_gt_u32 s42, 0x51ff
	s_cbranch_scc0 .LBB0_177
	s_cmpk_gt_u32 s42, 0x53ff
	s_cbranch_scc0 .LBB0_174
	s_cmpk_gt_u32 s42, 0x5bff
	s_cbranch_scc0 .LBB0_171
	s_cmpk_gt_u32 s42, 0x71ff
	s_cbranch_scc0 .LBB0_168
	v_mov_b32_e32 v32, s22
	ds_read_b64 v[32:33], v32
	s_cmpk_gt_u32 s42, 0x87ff
	s_mov_b64 s[4:5], -1
	s_cbranch_scc0 .LBB0_164
	v_mov_b32_e32 v34, s23
	ds_read_b64 v[34:35], v34
	s_add_i32 s43, s42, 0xffff7800
	s_waitcnt lgkmcnt(0)
	v_readfirstlane_b32 s16, v32
	v_readfirstlane_b32 s17, v33
	s_mov_b64 s[4:5], 0
	v_readfirstlane_b32 s0, v34
	v_readfirstlane_b32 s1, v35

; #define LAS __attribute__((address_space(3)))
; #define LDS_WAIT() asm volatile("s_waitcnt lgkmcnt(0)" ::: "memory")
; __device__ __forceinline__ unsigned pk2(float lo, float hi) { return f2bf(lo) | (f2bf(hi) << 16); }
; __device__ __forceinline__ void tr_store(const TrItem& t, int lane, const f32x4 (&r)[8], LAS float* scr) {
;     ...
;     const int c = lane & 7;
; #pragma unroll
;     for (int j = 0; j < 4; ++j) { const int n = (lane >> 3) + 8 * j; const LAS float* s = scr + (8 * c) * 33 + n;
;         v4u o; o.x = pk2(s[0 * 33], s[1 * 33]); o.y = pk2(s[2 * 33], s[3 * 33]); o.z = pk2(s[4 * 33], s[5 * 33]); o.w = pk2(s[6 * 33], s[7 * 33]);
;         const int nn = n0 + n; int drow = t.mode == 0 ? nn : ((nn >> 7) * 256 + (t.mode == 2 ? 128 : 0) + (nn & 127));
;         if (t.mode == 3) drow = nn < 2048 ? ((nn >> 8) * 256 + ((nn >> 5) & 1) * 128 + ((nn >> 6) & 3) * 32 + (nn & 31)) : nn;
;         *(v4u*)(t.WT + (size_t)drow * t.K + k0 + 8 * c) = o; }
;     LDS_WAIT(); asm volatile("" ::: "memory");
.LBB0_194:
	s_waitcnt lgkmcnt(3)
	v_bfe_u32 v86, v74, 16, 1
	v_add3_u32 v74, v74, v86, s38
	v_bfe_u32 v86, v75, 16, 1
	v_lshrrev_b32_e32 v74, 16, v74
	v_add3_u32 v75, v75, v86, s38
	v_and_or_b32 v86, v75, s39, v74
	s_waitcnt lgkmcnt(2)
	v_bfe_u32 v74, v72, 16, 1
	v_add3_u32 v72, v72, v74, s38
	v_bfe_u32 v74, v73, 16, 1
	v_lshrrev_b32_e32 v72, 16, v72
	v_add3_u32 v73, v73, v74, s38
	v_and_or_b32 v87, v73, s39, v72
	s_waitcnt lgkmcnt(1)
	v_bfe_u32 v72, v70, 16, 1
	v_add3_u32 v70, v70, v72, s38
	v_bfe_u32 v72, v71, 16, 1
	v_lshrrev_b32_e32 v70, 16, v70
	v_add3_u32 v71, v71, v72, s38
	v_and_or_b32 v88, v71, s39, v70
	s_waitcnt lgkmcnt(0)
	v_bfe_u32 v70, v68, 16, 1
	v_add3_u32 v68, v68, v70, s38
	v_bfe_u32 v70, v69, 16, 1
	v_lshrrev_b32_e32 v68, 16, v68
	v_add3_u32 v69, v69, v70, s38
	s_lshl_b32 s16, s16, 6
	v_and_or_b32 v89, v69, s39, v68
	v_mad_i64_i32 v[68:69], s[4:5], v67, s21, 0
	s_ashr_i32 s17, s16, 31
	v_lshl_add_u64 v[68:69], v[68:69], 1, s[8:9]
	v_lshl_add_u64 v[68:69], s[16:17], 1, v[68:69]
	v_lshl_add_u64 v[68:69], v[68:69], 0, v[64:65]
	global_store_dwordx4 v[68:69], v[86:89], off sc1
	ds_read2_b32 v[74:75], v80 offset0:8 offset1:41
	ds_read2_b32 v[72:73], v80 offset0:74 offset1:107
	ds_read2_b32 v[70:71], v80 offset0:140 offset1:173
	ds_read2_b32 v[68:69], v80 offset0:206 offset1:239
	v_cndmask_b32_e64 v67, 0, 1, s[18:19]
	v_cmp_ne_u32_e64 s[4:5], 1, v67
	s_andn2_b64 vcc, exec, s[18:19]
	v_add_u32_e32 v67, s46, v77
	s_cbranch_vccnz .LBB0_198
	v_cmp_gt_i32_e32 vcc, s37, v67
	s_and_saveexec_b64 s[18:19], vcc
	v_lshlrev_b32_e32 v86, 2, v67
	v_lshrrev_b32_e32 v87, 1, v67
	v_and_b32_e32 v86, 0x80, v86
	v_and_b32_e32 v87, 0x60, v87
	v_and_or_b32 v67, v67, s36, v82
	v_or3_b32 v67, v67, v86, v87
	s_or_b64 exec, exec, s[18:19]
	s_branch .LBB0_199

; #define LAS __attribute__((address_space(3)))
; #define LDS_WAIT() asm volatile("s_waitcnt lgkmcnt(0)" ::: "memory")
; __device__ __forceinline__ unsigned pk2(float lo, float hi) { return f2bf(lo) | (f2bf(hi) << 16); }
; __device__ __forceinline__ void tr_store(const TrItem& t, int lane, const f32x4 (&r)[8], LAS float* scr) {
;     ...
;     const int c = lane & 7;
; #pragma unroll
;     for (int j = 0; j < 4; ++j) { const int n = (lane >> 3) + 8 * j; const LAS float* s = scr + (8 * c) * 33 + n;
;         v4u o; o.x = pk2(s[0 * 33], s[1 * 33]); o.y = pk2(s[2 * 33], s[3 * 33]); o.z = pk2(s[4 * 33], s[5 * 33]); o.w = pk2(s[6 * 33], s[7 * 33]);
;         const int nn = n0 + n; int drow = t.mode == 0 ? nn : ((nn >> 7) * 256 + (t.mode == 2 ? 128 : 0) + (nn & 127));
;         if (t.mode == 3) drow = nn < 2048 ? ((nn >> 8) * 256 + ((nn >> 5) & 1) * 128 + ((nn >> 6) & 3) * 32 + (nn & 31)) : nn;
;         *(v4u*)(t.WT + (size_t)drow * t.K + k0 + 8 * c) = o; }
;     LDS_WAIT(); asm volatile("" ::: "memory");
.LBB0_199:
	s_waitcnt lgkmcnt(0)
	v_bfe_u32 v86, v74, 16, 1
	v_add3_u32 v74, v74, v86, s38
	v_bfe_u32 v86, v75, 16, 1
	v_lshrrev_b32_e32 v74, 16, v74
	v_add3_u32 v75, v75, v86, s38
	v_and_or_b32 v86, v75, s39, v74
	v_bfe_u32 v74, v72, 16, 1
	v_add3_u32 v72, v72, v74, s38
	v_bfe_u32 v74, v73, 16, 1
	v_lshrrev_b32_e32 v72, 16, v72
	v_add3_u32 v73, v73, v74, s38
	v_and_or_b32 v87, v73, s39, v72
	v_bfe_u32 v72, v70, 16, 1
	v_add3_u32 v70, v70, v72, s38
	v_bfe_u32 v72, v71, 16, 1
	v_lshrrev_b32_e32 v70, 16, v70
	v_add3_u32 v71, v71, v72, s38
	v_and_or_b32 v88, v71, s39, v70
	v_bfe_u32 v70, v68, 16, 1
	v_add3_u32 v68, v68, v70, s38
	v_bfe_u32 v70, v69, 16, 1
	v_lshrrev_b32_e32 v68, 16, v68
	v_add3_u32 v69, v69, v70, s38
	v_and_or_b32 v89, v69, s39, v68
	v_mad_i64_i32 v[68:69], s[18:19], v67, s21, 0
	v_lshl_add_u64 v[68:69], v[68:69], 1, s[8:9]
	v_lshl_add_u64 v[68:69], s[16:17], 1, v[68:69]
	v_lshl_add_u64 v[68:69], v[68:69], 0, v[64:65]
	global_store_dwordx4 v[68:69], v[86:89], off sc1
	ds_read2_b32 v[74:75], v80 offset0:16 offset1:49
	ds_read2_b32 v[72:73], v80 offset0:82 offset1:115
	ds_read2_b32 v[70:71], v80 offset0:148 offset1:181
	ds_read2_b32 v[68:69], v80 offset0:214 offset1:247
	s_and_b64 vcc, exec, s[4:5]
	v_add_u32_e32 v67, s46, v78
	s_cbranch_vccnz .LBB0_203
	v_cmp_gt_i32_e32 vcc, s37, v67
	s_and_saveexec_b64 s[18:19], vcc
	v_lshlrev_b32_e32 v86, 2, v67
	v_lshrrev_b32_e32 v87, 1, v67
	v_and_b32_e32 v86, 0x80, v86
	v_and_b32_e32 v87, 0x60, v87
	v_and_or_b32 v67, v67, s36, v83
	v_or3_b32 v67, v67, v86, v87
	s_or_b64 exec, exec, s[18:19]
	s_branch .LBB0_204

; #define LAS __attribute__((address_space(3)))
; #define LDS_WAIT() asm volatile("s_waitcnt lgkmcnt(0)" ::: "memory")
; __device__ __forceinline__ unsigned pk2(float lo, float hi) { return f2bf(lo) | (f2bf(hi) << 16); }
; __device__ __forceinline__ void tr_store(const TrItem& t, int lane, const f32x4 (&r)[8], LAS float* scr) {
;     ...
;     const int c = lane & 7;
; #pragma unroll
;     for (int j = 0; j < 4; ++j) { const int n = (lane >> 3) + 8 * j; const LAS float* s = scr + (8 * c) * 33 + n;
;         v4u o; o.x = pk2(s[0 * 33], s[1 * 33]); o.y = pk2(s[2 * 33], s[3 * 33]); o.z = pk2(s[4 * 33], s[5 * 33]); o.w = pk2(s[6 * 33], s[7 * 33]);
;         const int nn = n0 + n; int drow = t.mode == 0 ? nn : ((nn >> 7) * 256 + (t.mode == 2 ? 128 : 0) + (nn & 127));
;         if (t.mode == 3) drow = nn < 2048 ? ((nn >> 8) * 256 + ((nn >> 5) & 1) * 128 + ((nn >> 6) & 3) * 32 + (nn & 31)) : nn;
;         *(v4u*)(t.WT + (size_t)drow * t.K + k0 + 8 * c) = o; }
;     LDS_WAIT(); asm volatile("" ::: "memory");
.LBB0_204:
	s_waitcnt lgkmcnt(0)
	v_bfe_u32 v86, v74, 16, 1
	v_add3_u32 v74, v74, v86, s38
	v_bfe_u32 v86, v75, 16, 1
	v_lshrrev_b32_e32 v74, 16, v74
	v_add3_u32 v75, v75, v86, s38
	v_and_or_b32 v86, v75, s39, v74
	v_bfe_u32 v74, v72, 16, 1
	v_add3_u32 v72, v72, v74, s38
	v_bfe_u32 v74, v73, 16, 1
	v_lshrrev_b32_e32 v72, 16, v72
	v_add3_u32 v73, v73, v74, s38
	v_and_or_b32 v87, v73, s39, v72
	v_bfe_u32 v72, v70, 16, 1
	v_add3_u32 v70, v70, v72, s38
	v_bfe_u32 v72, v71, 16, 1
	v_lshrrev_b32_e32 v70, 16, v70
	v_add3_u32 v71, v71, v72, s38
	v_and_or_b32 v88, v71, s39, v70
	v_bfe_u32 v70, v68, 16, 1
	v_add3_u32 v68, v68, v70, s38
	v_bfe_u32 v70, v69, 16, 1
	v_lshrrev_b32_e32 v68, 16, v68
	v_add3_u32 v69, v69, v70, s38
	v_and_or_b32 v89, v69, s39, v68
	v_mad_i64_i32 v[68:69], s[18:19], v67, s21, 0
	v_lshl_add_u64 v[68:69], v[68:69], 1, s[8:9]
	v_lshl_add_u64 v[68:69], s[16:17], 1, v[68:69]
	v_lshl_add_u64 v[68:69], v[68:69], 0, v[64:65]
	global_store_dwordx4 v[68:69], v[86:89], off sc1
	ds_read2_b32 v[74:75], v80 offset0:24 offset1:57
	ds_read2_b32 v[72:73], v80 offset0:90 offset1:123
	ds_read2_b32 v[70:71], v80 offset0:156 offset1:189
	ds_read2_b32 v[68:69], v80 offset0:222 offset1:255
	s_and_b64 vcc, exec, s[4:5]
	v_add_u32_e32 v67, s46, v79
	s_cbranch_vccnz .LBB0_208
	v_cmp_gt_i32_e32 vcc, s37, v67
	s_and_saveexec_b64 s[0:1], vcc
	v_lshlrev_b32_e32 v86, 2, v67
	v_lshrrev_b32_e32 v87, 1, v67
	v_and_b32_e32 v86, 0x80, v86
	v_and_b32_e32 v87, 0x60, v87
	v_and_or_b32 v67, v67, s36, v84
	v_or3_b32 v67, v67, v86, v87
	s_or_b64 exec, exec, s[0:1]
	s_branch .LBB0_209

; #define LAS __attribute__((address_space(3)))
; #define LDS_WAIT() asm volatile("s_waitcnt lgkmcnt(0)" ::: "memory")
; __device__ __forceinline__ unsigned pk2(float lo, float hi) { return f2bf(lo) | (f2bf(hi) << 16); }
; __device__ __forceinline__ void tr_store(const TrItem& t, int lane, const f32x4 (&r)[8], LAS float* scr) {
;     ...
;     const int c = lane & 7;
; #pragma unroll
;     for (int j = 0; j < 4; ++j) { const int n = (lane >> 3) + 8 * j; const LAS float* s = scr + (8 * c) * 33 + n;
;         v4u o; o.x = pk2(s[0 * 33], s[1 * 33]); o.y = pk2(s[2 * 33], s[3 * 33]); o.z = pk2(s[4 * 33], s[5 * 33]); o.w = pk2(s[6 * 33], s[7 * 33]);
;         const int nn = n0 + n; int drow = t.mode == 0 ? nn : ((nn >> 7) * 256 + (t.mode == 2 ? 128 : 0) + (nn & 127));
;         if (t.mode == 3) drow = nn < 2048 ? ((nn >> 8) * 256 + ((nn >> 5) & 1) * 128 + ((nn >> 6) & 3) * 32 + (nn & 31)) : nn;
;         *(v4u*)(t.WT + (size_t)drow * t.K + k0 + 8 * c) = o; }
;     LDS_WAIT(); asm volatile("" ::: "memory");
; __global__ void __launch_bounds__(NTHR, 2) mk_fwd(Args args) {
;     ...
;                 tr_store(cur, lane, ra, scr);
;                 if (!has) break;
;                 it = itn; cur = nxt;
; #pragma unroll
;                 for (int i = 0; i < 8; ++i) ra[i] = rb[i]; } }
.LBB0_209:
	s_waitcnt lgkmcnt(0)
	v_bfe_u32 v86, v75, 16, 1
	v_add3_u32 v75, v75, v86, s38
	v_bfe_u32 v86, v74, 16, 1
	v_add3_u32 v74, v74, v86, s38
	v_lshrrev_b32_e32 v74, 16, v74
	v_and_or_b32 v86, v75, s39, v74
	v_bfe_u32 v74, v73, 16, 1
	v_add3_u32 v73, v73, v74, s38
	v_bfe_u32 v74, v72, 16, 1
	v_add3_u32 v72, v72, v74, s38
	v_lshrrev_b32_e32 v72, 16, v72
	v_and_or_b32 v87, v73, s39, v72
	v_bfe_u32 v72, v71, 16, 1
	v_add3_u32 v71, v71, v72, s38
	v_bfe_u32 v72, v70, 16, 1
	v_add3_u32 v70, v70, v72, s38
	v_lshrrev_b32_e32 v70, 16, v70
	v_and_or_b32 v88, v71, s39, v70
	v_bfe_u32 v70, v69, 16, 1
	v_add3_u32 v69, v69, v70, s38
	v_bfe_u32 v70, v68, 16, 1
	v_add3_u32 v68, v68, v70, s38
	v_lshrrev_b32_e32 v68, 16, v68
	v_and_or_b32 v89, v69, s39, v68
	v_mad_i64_i32 v[68:69], s[0:1], v67, s21, 0
	v_lshl_add_u64 v[68:69], v[68:69], 1, s[8:9]
	v_lshl_add_u64 v[68:69], s[16:17], 1, v[68:69]
	v_lshl_add_u64 v[68:69], v[68:69], 0, v[64:65]
	global_store_dwordx4 v[68:69], v[86:89], off sc1
	s_waitcnt lgkmcnt(0)
	s_andn2_b64 vcc, exec, s[12:13]
	s_cbranch_vccnz .LBB0_153
	v_mov_b64_e32 v[0:1], v[32:33]
	v_mov_b64_e32 v[4:5], v[36:37]
	v_mov_b64_e32 v[8:9], v[40:41]
	v_mov_b64_e32 v[12:13], v[44:45]
	v_mov_b64_e32 v[16:17], v[48:49]
	v_mov_b64_e32 v[20:21], v[52:53]
	v_mov_b64_e32 v[24:25], v[56:57]
	v_mov_b64_e32 v[28:29], v[60:61]
	v_mov_b64_e32 v[2:3], v[34:35]
	v_mov_b64_e32 v[6:7], v[38:39]
	v_mov_b64_e32 v[10:11], v[42:43]
	v_mov_b64_e32 v[14:15], v[46:47]
	v_mov_b64_e32 v[18:19], v[50:51]
	v_mov_b64_e32 v[22:23], v[54:55]
	v_mov_b64_e32 v[26:27], v[58:59]
	v_mov_b64_e32 v[30:31], v[62:63]
	s_mov_b64 s[8:9], s[14:15]
	s_mov_b32 s21, s45
	s_mov_b32 s40, s6
	s_mov_b32 s20, s44
	s_mov_b32 s3, s43
	s_mov_b32 s41, s42
	s_branch .LBB0_153
